# seam G2-P4 made XCC-local: gate_b relocated over U, V^T stored batch-major (both batch-aligned with what G2 reads)
# speedup vs baseline: 1.0444x; 1.0006x over previous
.LBB0_574:
	s_cmp_gt_i32 s95, 4
	s_cselect_b64 s[4:5], -1, 0
	s_and_b64 s[0:1], s[0:1], s[4:5]
	s_andn2_b64 vcc, exec, s[0:1]
	v_readlane_b32 s14, v245, 57
	s_cbranch_vccnz .LBB0_630
	s_waitcnt vmcnt(0)
	v_readlane_b32 s0, v245, 55
	v_readlane_b32 s1, v245, 56
	s_and_b64 vcc, exec, s[0:1]
	s_waitcnt vmcnt(0)
	s_barrier
	s_cbranch_vccnz .LBB0_629
	v_mbcnt_hi_u32_b32 v0, -1, v192
	v_cmp_eq_u32_e32 vcc, 0, v0
	s_and_saveexec_b64 s[0:1], vcc
	s_cbranch_execz .LBB0_628
	s_waitcnt vmcnt(0) lgkmcnt(0)
	v_mov_b32_e32 v1, 1
	v_readlane_b32 s11, v244, 43
	s_cmp_eq_u32 s11, 1
	s_cbranch_scc0 .Lxb3_glob
	s_and_b32 s12, s2, 7
	s_lshl_b32 s10, s12, 8
	s_add_i32 s10, s10, 0x6000
	v_mov_b32_e32 v6, s10
	global_atomic_add v6, v1, s[92:93]
	buffer_inv sc1
	v_readlane_b32 s11, v244, 41
	s_sub_i32 s11, s11, s12
	s_add_i32 s11, s11, 7
	s_lshr_b32 s11, s11, 3
	s_mul_i32 s6, s11, 3
	s_branch .Lxb3_wait

.LBB0_654:
	s_andn2_b64 vcc, exec, s[42:43]
	s_cbranch_vccnz .LBB0_656
	s_add_u32 s36, s92, 0xdd00000
	s_addc_u32 s37, s93, 0

.LBB0_680:
	s_lshr_b32 s0, s9, 3
	s_lshl_b32 s0, s0, 22
	s_add_u32 s0, s26, s0
	s_addc_u32 s1, s27, 0
	v_lshl_add_u32 v150, s8, 8, v144
	v_cvt_pk_bf16_f32 v68, v68, v69
	v_cvt_pk_bf16_f32 v69, v70, v71
	v_cvt_pk_bf16_f32 v70, v64, v65
	v_add_u32_e32 v64, 0x80, v150
	v_lshl_or_b32 v152, s9, 8, v146
	v_and_b32_e32 v152, 0x7ff, v152
	v_ashrrev_i32_e32 v151, 31, v150
	v_ashrrev_i32_e32 v65, 31, v64
	v_cvt_pk_bf16_f32 v124, v124, v125
	v_cvt_pk_bf16_f32 v125, v126, v127
	v_cvt_pk_bf16_f32 v126, v120, v121
	v_lshlrev_b64 v[120:121], 12, v[150:151]
	v_ashrrev_i32_e32 v153, 31, v152
	v_cvt_pk_bf16_f32 v60, v60, v61
	v_cvt_pk_bf16_f32 v61, v62, v63
	v_cvt_pk_bf16_f32 v62, v56, v57
	v_lshlrev_b64 v[56:57], 12, v[64:65]
	v_cvt_pk_bf16_f32 v127, v122, v123
	v_lshl_add_u64 v[120:121], s[0:1], 0, v[120:121]
	v_lshlrev_b64 v[122:123], 1, v[152:153]
	v_lshl_add_u64 v[56:57], s[0:1], 0, v[56:57]
	v_lshl_add_u64 v[120:121], v[120:121], 0, v[122:123]
	v_cvt_pk_bf16_f32 v108, v108, v109
	v_cvt_pk_bf16_f32 v109, v110, v111
	v_cvt_pk_bf16_f32 v110, v104, v105
	v_cvt_pk_bf16_f32 v111, v106, v107
	v_lshl_add_u64 v[56:57], v[56:57], 0, v[122:123]
	v_cvt_pk_bf16_f32 v44, v44, v45
	v_cvt_pk_bf16_f32 v45, v46, v47
	v_cvt_pk_bf16_f32 v46, v40, v41
	v_cvt_pk_bf16_f32 v47, v42, v43
	global_store_dwordx4 v[120:121], v[108:111], off offset:256
	global_store_dwordx4 v[56:57], v[44:47], off offset:256
	v_cvt_pk_bf16_f32 v92, v92, v93
	v_or_b32_e32 v108, 16, v150
	v_add_u32_e32 v44, 0x90, v150
	v_ashrrev_i32_e32 v109, 31, v108
	v_ashrrev_i32_e32 v45, 31, v44
	v_lshlrev_b64 v[108:109], 12, v[108:109]
	v_lshlrev_b64 v[44:45], 12, v[44:45]
	v_lshl_add_u64 v[108:109], s[0:1], 0, v[108:109]
	v_lshl_add_u64 v[44:45], s[0:1], 0, v[44:45]
	v_lshl_add_u64 v[108:109], v[108:109], 0, v[122:123]
	v_cvt_pk_bf16_f32 v93, v94, v95
	v_cvt_pk_bf16_f32 v94, v88, v89
	v_cvt_pk_bf16_f32 v95, v90, v91
	v_lshl_add_u64 v[44:45], v[44:45], 0, v[122:123]
	v_cvt_pk_bf16_f32 v28, v28, v29
	v_cvt_pk_bf16_f32 v29, v30, v31
	v_cvt_pk_bf16_f32 v30, v24, v25
	v_cvt_pk_bf16_f32 v31, v26, v27
	global_store_dwordx4 v[108:109], v[92:95], off offset:256
	global_store_dwordx4 v[44:45], v[28:31], off offset:256
	v_cvt_pk_bf16_f32 v76, v76, v77
	v_or_b32_e32 v92, 32, v150
	v_add_u32_e32 v28, 0xa0, v150
	v_ashrrev_i32_e32 v93, 31, v92
	v_ashrrev_i32_e32 v29, 31, v28
	v_lshlrev_b64 v[92:93], 12, v[92:93]
	v_lshlrev_b64 v[28:29], 12, v[28:29]
	v_lshl_add_u64 v[92:93], s[0:1], 0, v[92:93]
	v_lshl_add_u64 v[28:29], s[0:1], 0, v[28:29]
	v_lshl_add_u64 v[92:93], v[92:93], 0, v[122:123]
	v_cvt_pk_bf16_f32 v77, v78, v79
	v_cvt_pk_bf16_f32 v78, v72, v73
	v_cvt_pk_bf16_f32 v79, v74, v75
	v_lshl_add_u64 v[28:29], v[28:29], 0, v[122:123]
	v_cvt_pk_bf16_f32 v12, v12, v13
	v_cvt_pk_bf16_f32 v13, v14, v15
	v_cvt_pk_bf16_f32 v14, v8, v9
	v_cvt_pk_bf16_f32 v15, v10, v11
	global_store_dwordx4 v[92:93], v[76:79], off offset:256
	global_store_dwordx4 v[28:29], v[12:15], off offset:256
	v_cvt_pk_bf16_f32 v104, v116, v117
	v_or_b32_e32 v76, 48, v150
	v_add_u32_e32 v12, 0xb0, v150
	v_ashrrev_i32_e32 v77, 31, v76
	v_ashrrev_i32_e32 v13, 31, v12
	v_lshlrev_b64 v[76:77], 12, v[76:77]
	v_lshlrev_b64 v[12:13], 12, v[12:13]
	v_lshl_add_u64 v[76:77], s[0:1], 0, v[76:77]
	v_lshl_add_u64 v[12:13], s[0:1], 0, v[12:13]
	v_cvt_pk_bf16_f32 v105, v118, v119
	v_cvt_pk_bf16_f32 v106, v112, v113
	v_cvt_pk_bf16_f32 v107, v114, v115
	v_cvt_pk_bf16_f32 v88, v100, v101
	v_cvt_pk_bf16_f32 v89, v102, v103
	v_cvt_pk_bf16_f32 v90, v96, v97
	v_cvt_pk_bf16_f32 v91, v98, v99
	v_cvt_pk_bf16_f32 v72, v84, v85
	v_cvt_pk_bf16_f32 v73, v86, v87
	v_cvt_pk_bf16_f32 v74, v80, v81
	v_cvt_pk_bf16_f32 v75, v82, v83
	v_lshl_add_u64 v[76:77], v[76:77], 0, v[122:123]
	v_cvt_pk_bf16_f32 v71, v66, v67
	v_cvt_pk_bf16_f32 v63, v58, v59
	v_cvt_pk_bf16_f32 v40, v52, v53
	v_cvt_pk_bf16_f32 v41, v54, v55
	v_cvt_pk_bf16_f32 v42, v48, v49
	v_cvt_pk_bf16_f32 v43, v50, v51
	v_cvt_pk_bf16_f32 v24, v36, v37
	v_cvt_pk_bf16_f32 v25, v38, v39
	v_cvt_pk_bf16_f32 v26, v32, v33
	v_cvt_pk_bf16_f32 v27, v34, v35
	v_cvt_pk_bf16_f32 v8, v20, v21
	v_cvt_pk_bf16_f32 v9, v22, v23
	v_cvt_pk_bf16_f32 v10, v16, v17
	v_cvt_pk_bf16_f32 v11, v18, v19
	v_lshl_add_u64 v[12:13], v[12:13], 0, v[122:123]
	v_cvt_pk_bf16_f32 v4, v4, v5
	v_cvt_pk_bf16_f32 v5, v6, v7
	v_cvt_pk_bf16_f32 v6, v0, v1
	v_cvt_pk_bf16_f32 v7, v2, v3
	s_andn2_b64 vcc, exec, s[38:39]
	s_mov_b64 s[8:9], -1
	global_store_dwordx4 v[120:121], v[124:127], off
	global_store_dwordx4 v[108:109], v[104:107], off
	global_store_dwordx4 v[92:93], v[88:91], off
	global_store_dwordx4 v[76:77], v[72:75], off
	global_store_dwordx4 v[76:77], v[68:71], off offset:256
	global_store_dwordx4 v[56:57], v[60:63], off
	global_store_dwordx4 v[44:45], v[40:43], off
	global_store_dwordx4 v[28:29], v[24:27], off
	global_store_dwordx4 v[12:13], v[8:11], off
	global_store_dwordx4 v[12:13], v[4:7], off offset:256
	s_cbranch_vccnz .LBB0_669
	s_andn2_b64 vcc, exec, s[0:1]
	s_cbranch_vccnz .LBB0_668
	s_barrier
	s_branch .LBB0_668

.LBB0_684:
	s_cmp_gt_i32 s95, 5
	s_cselect_b64 s[0:1], -1, 0
	s_and_b64 s[4:5], s[40:41], s[0:1]
	v_readlane_b32 s64, v245, 53
	s_andn2_b64 vcc, exec, s[4:5]
	v_readlane_b32 s65, v245, 54
	s_cbranch_vccnz .LBB0_740
	s_waitcnt vmcnt(0)
	v_readlane_b32 s4, v245, 55
	v_readlane_b32 s5, v245, 56
	s_and_b64 vcc, exec, s[4:5]
	s_waitcnt vmcnt(0)
	s_barrier
	s_cbranch_vccnz .LBB0_739
	v_mbcnt_hi_u32_b32 v0, -1, v192
	v_cmp_eq_u32_e32 vcc, 0, v0
	s_and_saveexec_b64 s[4:5], vcc
	s_cbranch_execz .LBB0_738
	s_waitcnt vmcnt(0) lgkmcnt(0)
	v_mov_b32_e32 v1, 1
	v_readlane_b32 s11, v244, 43
	s_cmp_eq_u32 s11, 1
	s_cbranch_scc0 .Lxb4_glob
	s_and_b32 s12, s2, 7
	s_lshl_b32 s10, s12, 8
	s_add_i32 s10, s10, 0x6000
	v_mov_b32_e32 v6, s10
	global_atomic_add v6, v1, s[92:93]
	buffer_inv sc1
	v_readlane_b32 s11, v244, 41
	s_sub_i32 s11, s11, s12
	s_add_i32 s11, s11, 7
	s_lshr_b32 s11, s11, 3
	s_mul_i32 s6, s11, 4
	s_branch .Lxb4_wait

.Lattn_main:
	v_writelane_b32 v244, s79, 16
	v_mov_b32_e32 v203, v97
	v_mov_b32_e32 v248, v247
	v_mov_b32_e32 v249, v247
	v_mov_b32_e32 v250, v247
	v_mov_b32_e32 v251, v247
	v_mbcnt_hi_u32_b32 v204, -1, v192
	v_readlane_b32 s4, v245, 0
	v_readlane_b32 s0, v245, 7
	s_lshr_b32 s6, s4, 6
	s_mov_b32 s4, s62
	s_mov_b32 s5, s63
	s_cmp_eq_u32 s0, 0x100
	s_cselect_b32 s7, 1, 0
	s_mov_b32 s78, s0
	s_add_u32 s8, s92, 0x6d00000
	s_addc_u32 s9, s93, 0
	s_add_u32 s10, s92, 0x8d00000
	s_addc_u32 s11, s93, 0
	s_add_u32 s12, s92, 0xad00000
	s_addc_u32 s13, s93, 0
	s_add_u32 s14, s92, 0x4d00000
	s_addc_u32 s15, s93, 0
	s_add_u32 s16, s92, 0xdd00000
	s_addc_u32 s17, s93, 0
	s_add_u32 s18, s74, 0x2000000
	s_addc_u32 s19, s75, 0
	v_and_b32_e32 v205, 15, v204
	v_lshrrev_b32_e32 v206, 4, v204
	v_xor_b32_e32 v208, 16, v204
	v_lshlrev_b32_e32 v208, 2, v208
	v_xor_b32_e32 v209, 32, v204
	v_lshlrev_b32_e32 v209, 2, v209
	v_mov_b32_e32 v201, 0xf149f2ca
	v_lshlrev_b32_e32 v216, 4, v206
	v_and_b32_e32 v207, 3, v205
	v_xor_b32_e32 v207, v207, v206
	v_lshlrev_b32_e32 v207, 4, v207
	v_lshl_add_u32 v207, v205, 8, v207
	v_lshrrev_b32_e32 v217, 2, v205
	v_xor_b32_e32 v218, 0, v217
	v_lshl_add_u32 v195, v218, 6, v207
	v_xor_b32_e32 v218, 1, v217
	v_lshl_add_u32 v196, v218, 6, v207
	v_xor_b32_e32 v218, 2, v217
	v_lshl_add_u32 v231, v218, 6, v207
	v_xor_b32_e32 v218, 3, v217
	v_lshl_add_u32 v232, v218, 6, v207
	v_bfe_u32 v217, v205, 1, 3
	v_and_b32_e32 v207, 3, v217
	v_xor_b32_e32 v207, v207, v206
	v_lshlrev_b32_e32 v207, 4, v207
	v_lshl_add_u32 v207, v205, 7, v207
	v_lshrrev_b32_e32 v217, 2, v217
	v_xor_b32_e32 v218, 0, v217
	v_lshl_add_u32 v233, v218, 6, v207
	v_xor_b32_e32 v218, 1, v217
	v_lshl_add_u32 v234, v218, 6, v207
	s_and_b32 s1, s6, 3
	s_lshl_b32 s40, s1, 12
	s_cmp_lt_u32 s6, 4
	s_cbranch_scc0 .Lattn_roleV
	v_lshrrev_b32_e32 v207, 4, v204
	v_and_b32_e32 v217, 15, v204
	v_xor_b32_e32 v217, v217, v207
	v_xor_b32_e32 v218, 0, v217
	v_lshlrev_b32_e32 v218, 4, v218
	v_add_u32_e32 v219, 0, v207
	v_lshl_add_u32 v197, v219, 11, v218
	v_xor_b32_e32 v218, 4, v217
	v_lshlrev_b32_e32 v218, 4, v218
	v_add_u32_e32 v219, 8, v207
	v_lshl_add_u32 v198, v219, 11, v218
	v_xor_b32_e32 v218, 8, v217
	v_lshlrev_b32_e32 v218, 4, v218
	v_add_u32_e32 v219, 16, v207
	v_lshl_add_u32 v229, v219, 11, v218
	v_xor_b32_e32 v218, 12, v217
	v_lshlrev_b32_e32 v218, 4, v218
	v_add_u32_e32 v219, 24, v207
	v_lshl_add_u32 v230, v219, 11, v218
	s_mov_b32 s86, s10
	s_mov_b32 s87, s11
	s_mov_b32 s41, 0x20000
	s_branch .Lattn_roleDone
.Lattn_roleV:
	v_lshrrev_b32_e32 v207, 3, v204
	v_and_b32_e32 v217, 7, v204
	v_add_u32_e32 v219, 0, v207
	v_bfe_u32 v218, v219, 1, 3
	v_xor_b32_e32 v218, v218, v217
	v_lshlrev_b32_e32 v218, 4, v218
	v_add_u32_e32 v219, 0, v219
	v_lshl_add_u32 v197, v219, 12, v218
	v_add_u32_e32 v219, 8, v207
	v_bfe_u32 v218, v219, 1, 3
	v_xor_b32_e32 v218, v218, v217
	v_lshlrev_b32_e32 v218, 4, v218
	v_add_u32_e32 v219, 0, v219
	v_lshl_add_u32 v198, v219, 12, v218
	v_add_u32_e32 v219, 0, v207
	v_bfe_u32 v218, v219, 1, 3
	v_xor_b32_e32 v218, v218, v217
	v_lshlrev_b32_e32 v218, 4, v218
	v_add_u32_e32 v219, 16, v219
	v_lshl_add_u32 v229, v219, 12, v218
	v_add_u32_e32 v219, 8, v207
	v_bfe_u32 v218, v219, 1, 3
	v_xor_b32_e32 v218, v218, v217
	v_lshlrev_b32_e32 v218, 4, v218
	v_add_u32_e32 v219, 16, v219
	v_lshl_add_u32 v230, v219, 12, v218
	s_mov_b32 s86, s12
	s_mov_b32 s87, s13
	s_movk_i32 s41, 0x80
	s_or_b32 s40, s40, 0x4000

.Lat_ubV2:
	s_and_b32 s0, s6, 3
	s_lshl_b32 s0, s0, 5
	s_lshl_b32 s1, s33, 7
	s_add_i32 s0, s0, s1
	s_lshl_b32 s0, s0, 12
	s_lshl_b32 s1, s23, 22
	s_add_i32 s79, s0, s1

.LBB0_908:
	s_cmp_gt_i32 s95, 7
	s_cselect_b64 s[4:5], -1, 0
	s_and_b64 s[0:1], s[0:1], s[4:5]
	s_andn2_b64 vcc, exec, s[0:1]
	s_cbranch_vccnz .LBB0_964
	s_waitcnt vmcnt(0)
	v_readlane_b32 s0, v245, 55
	v_readlane_b32 s1, v245, 56
	s_and_b64 vcc, exec, s[0:1]
	s_waitcnt lgkmcnt(0)
	s_barrier
	s_cbranch_vccnz .LBB0_963
	v_mbcnt_hi_u32_b32 v0, -1, v192
	v_cmp_eq_u32_e32 vcc, 0, v0
	s_and_saveexec_b64 s[0:1], vcc
	s_cbranch_execz .LBB0_962
	s_waitcnt vmcnt(0) lgkmcnt(0)
	v_mov_b32_e32 v1, 1
	v_readlane_b32 s11, v244, 43
	s_cmp_eq_u32 s11, 1
	s_cbranch_scc0 .Lxb6_glob
	s_and_b32 s12, s2, 7
	s_lshl_b32 s10, s12, 8
	s_add_i32 s10, s10, 0x6000
	v_mov_b32_e32 v6, s10
	global_atomic_add v6, v1, s[92:93]
	buffer_inv sc1
	v_readlane_b32 s11, v244, 41
	s_sub_i32 s11, s11, s12
	s_add_i32 s11, s11, 7
	s_lshr_b32 s11, s11, 3
	s_mul_i32 s6, s11, 5
	s_branch .Lxb6_wait

.LBB0_981:
	s_cmp_gt_i32 s95, 8
	s_cselect_b64 s[4:5], -1, 0
	s_and_b64 s[0:1], s[0:1], s[4:5]
	s_andn2_b64 vcc, exec, s[0:1]
	s_cbranch_vccnz .LBB0_1037
	s_waitcnt vmcnt(0)
	v_readlane_b32 s0, v245, 55
	v_readlane_b32 s1, v245, 56
	s_and_b64 vcc, exec, s[0:1]
	s_waitcnt lgkmcnt(0)
	s_barrier
	s_cbranch_vccnz .LBB0_1036
	v_mbcnt_hi_u32_b32 v0, -1, v192
	v_cmp_eq_u32_e32 vcc, 0, v0
	s_and_saveexec_b64 s[0:1], vcc
	s_cbranch_execz .LBB0_1035
	s_waitcnt vmcnt(0) lgkmcnt(0)
	v_mov_b32_e32 v1, 1
	v_readlane_b32 s11, v244, 43
	s_cmp_eq_u32 s11, 1
	s_cbranch_scc0 .Lxb7_glob
	s_and_b32 s12, s2, 7
	s_lshl_b32 s10, s12, 8
	s_add_i32 s10, s10, 0x6000
	v_mov_b32_e32 v6, s10
	global_atomic_add v6, v1, s[92:93]
	buffer_inv sc1
	v_readlane_b32 s11, v244, 41
	s_sub_i32 s11, s11, s12
	s_add_i32 s11, s11, 7
	s_lshr_b32 s11, s11, 3
	s_mul_i32 s6, s11, 6
	s_branch .Lxb7_wait
